# seam: non-leader arrival-counter poll back-off s_sleep 1 -> 6 (fewer polls contending with leader atomics)
# speedup vs baseline: 1.0131x; 1.0131x over previous
.LBB0_823:
	s_and_b32 s1, s0, 0xff
	s_mov_b64 s[20:21], -1
	s_cmp_lg_u32 s1, 0
	s_mov_b64 s[26:27], -1
	s_sleep 6
	s_cbranch_scc0 .LBB0_826
	s_and_b64 vcc, exec, s[26:27]
	s_cbranch_vccz .LBB0_822
